# same as the split-phase version with the spin bounds of the added waits raised to the baseline barrier's cap (2^18)
# baseline (speedup 1.0000x reference)
; #define SEAM(k) do { if ((k) < 2) xcd_barrier(bar); else xcd_barrier(barg); } while (0)
; __global__ void __launch_bounds__(NWAVES * 64, 2) fwd(Args a) {
;     ...
;     SEAM(0);
.Lp1_spin:
	global_load_dword v244, v[242:243], off sc1
	s_waitcnt vmcnt(0)
	v_cmp_lt_u32_e32 vcc, v244, v241
	s_cbranch_vccz .Lp1_released
	s_sleep 1
	s_add_i32 s13, s13, 1
	s_cmp_lt_u32 s13, 0x40000
	s_cbranch_scc1 .Lp1_spin

; #define SEAM(k) do { if ((k) < 2) xcd_barrier(bar); else xcd_barrier(barg); } while (0)
; __global__ void __launch_bounds__(NWAVES * 64, 2) fwd(Args a) {
;     ...
;     SEAM(4);
.Lq4_spin:
	global_load_dword v3, v1, s[4:5] sc1
	s_waitcnt vmcnt(0)
	v_cmp_gt_u32_e32 vcc, 4, v3
	s_cbranch_vccz .Lq4_ok
	s_sleep 1
	s_add_i32 s7, s7, 1
	s_cmp_lt_u32 s7, 0x40000
	s_cbranch_scc1 .Lq4_spin

; #define SEAM(k) do { if ((k) < 2) xcd_barrier(bar); else xcd_barrier(barg); } while (0)
; __global__ void __launch_bounds__(NWAVES * 64, 2) fwd(Args a) {
;     ...
;     SEAM(5);
.Lq5a_spin:
	global_load_dword v3, v1, s[4:5] sc1
	s_waitcnt vmcnt(0)
	v_cmp_gt_u32_e32 vcc, 4, v3
	s_cbranch_vccz .Lq5a_ok
	s_sleep 1
	s_add_i32 s9, s9, 1
	s_cmp_lt_u32 s9, 0x40000
	s_cbranch_scc1 .Lq5a_spin
